# kernel-argument lines re-read into the scalar cache by one wave while the workgroup waits in each grid barrier
# speedup vs baseline: 1.0897x; 1.0079x over previous
; DI unsigned xb_ld(unsigned* p)              { return __hip_atomic_load(p, __ATOMIC_RELAXED, __HIP_MEMORY_SCOPE_AGENT); }
; DI void xcd_barrier_complete(unsigned* bar, unsigned x, unsigned& nloc, unsigned& nx) {
;     const unsigned G = gridDim.x * gridDim.y * gridDim.z;
;     unsigned sum, cnt, mine, sp = 0u;
;     for (;;) {
;         sum = 0u; cnt = 0u; mine = 0u;
; #pragma unroll
;         for (unsigned j = 0; j < 16; ++j) { const unsigned c = xb_ld(&bar[XB_XCNT(j)]); sum += c; cnt += (c > 0u) ? 1u : 0u; mine = (j == x) ? c : mine; }
;         if (sum == G) break;
;         __builtin_amdgcn_s_sleep(1);
;         if ((++sp & 255u) == 0u) { if (xb_ld(&bar[XB_TMO])) break; if (sp > XB_SPIN_CAP) { atomicAdd(&bar[XB_TMO], 1u); break; } }
;     }
;     nloc = mine > 0u ? mine : 1u; nx = cnt > 0u ? cnt : 1u;
; }
; DI void xcd_barrier(const XcdBarrier& b) {
;     asm volatile("s_waitcnt vmcnt(0)" ::: "memory");
;     __syncthreads();
;     if (threadIdx.x == 0) {
;         unsigned* bar = b.bar;
;         __builtin_amdgcn_s_waitcnt(0);
;         unsigned nloc = b.st[0], nx = b.st[1];
;         if (nloc == 0u) { xcd_barrier_complete(bar, b.x, nloc, nx); b.st[0] = nloc; b.st[1] = nx; }
.LBB0_86:
	s_or_b64 exec, exec, s[6:7]
	s_waitcnt vmcnt(0)
	s_barrier
	v_readfirstlane_b32 s84, v203
	s_lshr_b32 s84, s84, 6
	s_cmp_eq_u32 s84, 1
	s_cbranch_scc0 .Lka_skip_0
	s_load_dwordx16 s[84:99], s[0:1], 0x0
	s_load_dwordx16 s[84:99], s[0:1], 0x40
	s_load_dwordx16 s[84:99], s[0:1], 0x80
	s_load_dwordx16 s[84:99], s[0:1], 0xc0
.Lka_skip_0:
	s_mov_b64 s[4:5], exec
	v_readlane_b32 s6, v255, 0
	v_readlane_b32 s7, v255, 1
	s_and_b64 s[6:7], s[4:5], s[6:7]
	s_mov_b64 exec, s[6:7]
	s_cbranch_execz .LBB0_138
	s_add_i32 s6, 0, 0x26100
	v_mov_b32_e32 v0, s6
	s_waitcnt vmcnt(0) expcnt(0) lgkmcnt(0)
	ds_read_b32 v2, v0
	s_add_i32 s6, 0, 0x26104
	v_mov_b32_e32 v0, s6
	ds_read_b32 v0, v0
	s_waitcnt lgkmcnt(1)
	v_cmp_ne_u32_e32 vcc, 0, v2
	s_cbranch_vccnz .LBB0_102
	v_readlane_b32 s6, v255, 2
	v_readlane_b32 s7, v255, 3
	s_load_dwordx2 s[10:11], s[6:7], 0x4
	s_add_u32 s6, s44, 0xf690200
	s_addc_u32 s7, s45, 0
	s_add_u32 s8, s44, 0xf690400
	s_addc_u32 s9, s45, 0
	s_waitcnt lgkmcnt(0)
	s_mul_i32 s38, s10, s3
	s_add_u32 s10, s44, 0xf690500
	s_mul_i32 s38, s38, s11
	s_addc_u32 s11, s45, 0
	s_add_u32 s12, s44, 0xf690600
	s_addc_u32 s13, s45, 0
	s_add_u32 s14, s44, 0xf690700
	s_addc_u32 s15, s45, 0
	s_add_u32 s16, s44, 0xf690800
	s_addc_u32 s17, s45, 0
	s_add_u32 s18, s44, 0xf690900
	s_addc_u32 s19, s45, 0
	s_add_u32 s20, s44, 0xf690a00
	s_addc_u32 s21, s45, 0
	s_add_u32 s22, s44, 0xf690b00
	s_addc_u32 s23, s45, 0
	s_add_u32 s24, s44, 0xf690c00
	s_addc_u32 s25, s45, 0
	s_add_u32 s26, s44, 0xf690d00
	s_addc_u32 s27, s45, 0
	s_add_u32 s28, s44, 0xf690e00
	s_addc_u32 s29, s45, 0
	s_add_u32 s30, s44, 0xf690f00
	s_addc_u32 s31, s45, 0
	s_add_u32 s34, s44, 0xf691000
	s_addc_u32 s35, s45, 0
	s_add_u32 s36, s44, 0xf691100
	s_addc_u32 s37, s45, 0
	s_add_u32 s40, s44, 0xf691200
	s_addc_u32 s41, s45, 0
	s_add_u32 s42, s44, 0xf691300
	s_addc_u32 s43, s45, 0
	s_mov_b32 s39, 1
	v_mov_b32_e32 v16, 0
	s_branch .LBB0_90

; DI void xcd_barrier(const XcdBarrier& b) {
;     asm volatile("s_waitcnt vmcnt(0)" ::: "memory");
;     __syncthreads();
.LBB0_855:
	s_waitcnt vmcnt(0)
	s_waitcnt vmcnt(0) lgkmcnt(0)
	s_barrier
	v_readfirstlane_b32 s84, v203
	s_lshr_b32 s84, s84, 6
	s_cmp_eq_u32 s84, 1
	s_cbranch_scc0 .Lka_skip_1
	s_load_dwordx16 s[84:99], s[0:1], 0x0
	s_load_dwordx16 s[84:99], s[0:1], 0x40
	s_load_dwordx16 s[84:99], s[0:1], 0x80
	s_load_dwordx16 s[84:99], s[0:1], 0xc0

; DI void xcd_barrier(const XcdBarrier& b) {
;     asm volatile("s_waitcnt vmcnt(0)" ::: "memory");
;     __syncthreads();
.LBB0_1011:
	s_waitcnt vmcnt(0)
	s_waitcnt lgkmcnt(0)
	s_barrier
	v_readfirstlane_b32 s84, v203
	s_lshr_b32 s84, s84, 6
	s_cmp_eq_u32 s84, 1
	s_cbranch_scc0 .Lka_skip_2
	s_load_dwordx16 s[84:99], s[0:1], 0x0
	s_load_dwordx16 s[84:99], s[0:1], 0x40
	s_load_dwordx16 s[84:99], s[0:1], 0x80
	s_load_dwordx16 s[84:99], s[0:1], 0xc0

; DI void xcd_barrier(const XcdBarrier& b) {
;     asm volatile("s_waitcnt vmcnt(0)" ::: "memory");
;     __syncthreads();
.LBB0_1076:
	s_waitcnt vmcnt(0)
	s_barrier
	v_readfirstlane_b32 s84, v203
	s_lshr_b32 s84, s84, 6
	s_cmp_eq_u32 s84, 1
	s_cbranch_scc0 .Lka_skip_3
	s_load_dwordx16 s[84:99], s[0:1], 0x0
	s_load_dwordx16 s[84:99], s[0:1], 0x40
	s_load_dwordx16 s[84:99], s[0:1], 0x80
	s_load_dwordx16 s[84:99], s[0:1], 0xc0

; DI unsigned xb_ld(unsigned* p)              { return __hip_atomic_load(p, __ATOMIC_RELAXED, __HIP_MEMORY_SCOPE_AGENT); }
; DI void xcd_barrier_complete(unsigned* bar, unsigned x, unsigned& nloc, unsigned& nx) {
;     const unsigned G = gridDim.x * gridDim.y * gridDim.z;
;     unsigned sum, cnt, mine, sp = 0u;
;     for (;;) {
;         sum = 0u; cnt = 0u; mine = 0u;
; #pragma unroll
;         for (unsigned j = 0; j < 16; ++j) { const unsigned c = xb_ld(&bar[XB_XCNT(j)]); sum += c; cnt += (c > 0u) ? 1u : 0u; mine = (j == x) ? c : mine; }
;         if (sum == G) break;
;         __builtin_amdgcn_s_sleep(1);
;         if ((++sp & 255u) == 0u) { if (xb_ld(&bar[XB_TMO])) break; if (sp > XB_SPIN_CAP) { atomicAdd(&bar[XB_TMO], 1u); break; } }
;     }
;     nloc = mine > 0u ? mine : 1u; nx = cnt > 0u ? cnt : 1u;
; }
; DI void xcd_barrier(const XcdBarrier& b) {
;     asm volatile("s_waitcnt vmcnt(0)" ::: "memory");
;     __syncthreads();
;     if (threadIdx.x == 0) {
;         unsigned* bar = b.bar;
;         __builtin_amdgcn_s_waitcnt(0);
;         unsigned nloc = b.st[0], nx = b.st[1];
;         if (nloc == 0u) { xcd_barrier_complete(bar, b.x, nloc, nx); b.st[0] = nloc; b.st[1] = nx; }
.Lka_skip_5:
	s_mov_b64 s[6:7], exec
	v_readlane_b32 s8, v255, 0
	v_readlane_b32 s9, v255, 1
	s_and_b64 s[8:9], s[6:7], s[8:9]
	s_mov_b64 exec, s[8:9]
	s_cbranch_execz .LBB0_1359
	s_add_i32 s8, 0, 0x26100
	v_mov_b32_e32 v0, s8
	s_waitcnt vmcnt(0) expcnt(0) lgkmcnt(0)
	ds_read_b32 v2, v0
	s_add_i32 s8, 0, 0x26104
	v_mov_b32_e32 v0, s8
	ds_read_b32 v0, v0
	s_waitcnt lgkmcnt(1)
	v_cmp_ne_u32_e32 vcc, 0, v2
	s_cbranch_vccnz .LBB0_1323
	v_readlane_b32 s8, v255, 2
	v_readlane_b32 s9, v255, 3
	s_load_dwordx2 s[12:13], s[8:9], 0x4
	s_add_u32 s8, s44, 0xf690200
	s_addc_u32 s9, s45, 0
	s_add_u32 s10, s44, 0xf690400
	s_addc_u32 s11, s45, 0
	s_waitcnt lgkmcnt(0)
	s_mul_i32 s54, s12, s3
	s_add_u32 s12, s44, 0xf690500
	s_mul_i32 s54, s54, s13
	s_addc_u32 s13, s45, 0
	s_add_u32 s14, s44, 0xf690600
	s_addc_u32 s15, s45, 0
	s_add_u32 s16, s44, 0xf690700
	s_addc_u32 s17, s45, 0
	s_add_u32 s18, s44, 0xf690800
	s_addc_u32 s19, s45, 0
	s_add_u32 s20, s44, 0xf690900
	s_addc_u32 s21, s45, 0
	s_add_u32 s22, s44, 0xf690a00
	s_addc_u32 s23, s45, 0
	s_add_u32 s24, s44, 0xf690b00
	s_addc_u32 s25, s45, 0
	s_add_u32 s26, s44, 0xf690c00
	s_addc_u32 s27, s45, 0
	s_add_u32 s28, s44, 0xf690d00
	s_addc_u32 s29, s45, 0
	s_add_u32 s30, s44, 0xf690e00
	s_addc_u32 s31, s45, 0
	s_add_u32 s34, s44, 0xf690f00
	s_addc_u32 s35, s45, 0
	s_add_u32 s36, s44, 0xf691000
	s_addc_u32 s37, s45, 0
	s_add_u32 s38, s44, 0xf691100
	s_addc_u32 s39, s45, 0
	s_add_u32 s40, s44, 0xf691200
	s_addc_u32 s41, s45, 0
	s_add_u32 s42, s44, 0xf691300
	s_addc_u32 s43, s45, 0
	s_mov_b32 s55, 1
	v_mov_b32_e32 v16, 0
	s_branch .LBB0_1311
